# P2: k_rope units skip the MFMAs of their all-zero B half; schedule rebalanced (k_rope CUs take 2 small units, all others 4)
# baseline (speedup 1.0000x reference)
;     __device__ bool next(int i, Unit& u) const { if (i >= 2) return false; const int j = c >> 3; u.pm = i * 32 + (c & 7) * 4 + (j >> 3); u.pn = j & 7; u.ty = 0; return true; }
;     __device__ static void small(int s, Unit& u) { if (s < 384) { u.ty = 0; u.pm = s / 6; u.pn = s % 6; } else { s -= 384; u.ty = 1; u.pm = s >> 3; u.pn = s & 7; } }
;     __device__ bool next(int i, Unit& u) const {
;         if (G == 256) {
;             if (c < 64) { if (i == 0) { u.ty = 2; u.pm = c; u.pn = 0; return true; } if (i == 1) { small(c, u); return true; } return false; }
;             const int k = c - 64, cnt = (k < 64) ? 5 : 4, start = (k < 64) ? 64 + 5 * k : 384 + 4 * (k - 64);
;             if (i >= cnt) return false; small(start + i, u); return true;
;         }
;         const int L = i * G + c; if (L >= 960) return false;
;         if (L < 64) { u.ty = 2; u.pm = L; u.pn = 0; } else small(L - 64, u);
;         return true;
;     }
.LBB0_367:
	s_cmp_lt_i32 s30, 3
	s_cselect_b64 s[4:5], -1, 0
	s_add_u32 s22, s28, 0x900000
	s_addc_u32 s23, s29, 0
	s_add_u32 s14, s28, 0x15f00000
	s_addc_u32 s15, s29, 0
	s_add_u32 s36, s28, 0x18f00000
	s_addc_u32 s37, s29, 0
	s_and_b64 s[40:41], s[4:5], s[0:1]
	s_andn2_b64 vcc, exec, s[40:41]
	s_cbranch_vccnz .LBB0_687
	s_cmpk_lg_i32 s33, 0x100
	s_cselect_b64 s[8:9], -1, 0
	s_cmp_gt_i32 s96, 63
	s_cselect_b64 s[0:1], -1, 0
	v_writelane_b32 v247, s0, 23
	v_readfirstlane_b32 s34, v0
	s_nop 0
	v_writelane_b32 v247, s1, 24
	s_lshl_b32 s0, s96, 2
	s_add_i32 s3, s0, 0xffffff80
	s_mul_i32 s0, s96, 5
	s_add_i32 s6, s0, 0xffffff00
	s_cmpk_lt_u32 s96, 0x80
	s_cselect_b64 s[4:5], -1, 0
	s_and_b64 s[0:1], s[4:5], exec
	s_cselect_b32 s73, s3, s3
	v_writelane_b32 v247, s8, 25
	s_and_b64 vcc, exec, s[8:9]
	s_nop 0
	v_writelane_b32 v247, s9, 26
	s_cbranch_vccz .LBB0_372
	s_mov_b64 s[0:1], 0
	s_cmpk_gt_i32 s96, 0x3bf
	s_mov_b64 s[6:7], 0
	s_cbranch_scc1 .LBB0_373
	v_readlane_b32 s6, v247, 23
	v_readlane_b32 s7, v247, 24
	s_andn2_b64 vcc, exec, s[6:7]
	s_cbranch_vccnz .LBB0_378
	s_sub_i32 s3, s96, 64
	s_add_i32 s6, s96, 0xfffffe40
	s_lshr_b32 s8, s6, 3
	s_mul_i32 s6, s3, 0xaaab
	s_lshr_b32 s10, s6, 18
	s_mul_i32 s6, s10, 6
	s_sub_i32 s6, s3, s6
	s_and_b32 s9, s96, 7
	s_and_b32 s11, s6, 0xffff
	s_cmpk_gt_u32 s3, 0x17f
	s_cselect_b64 s[6:7], -1, 0
	v_cndmask_b32_e64 v1, 0, 1, s[6:7]
	s_and_b64 s[6:7], s[6:7], exec
	v_readfirstlane_b32 s42, v1
	s_cselect_b32 s66, s9, s11
	s_cselect_b32 s48, s8, s10
	s_mov_b64 s[6:7], -1
	s_andn2_b64 vcc, exec, s[0:1]
	s_cbranch_vccz .LBB0_374
	s_branch .LBB0_382

;     __device__ bool next(int i, Unit& u) const { if (i >= 2) return false; const int j = c >> 3; u.pm = i * 32 + (c & 7) * 4 + (j >> 3); u.pn = j & 7; u.ty = 0; return true; }
;     __device__ static void small(int s, Unit& u) { if (s < 384) { u.ty = 0; u.pm = s / 6; u.pn = s % 6; } else { s -= 384; u.ty = 1; u.pm = s >> 3; u.pn = s & 7; } }
;     __device__ __forceinline__ void prep(const Unit& u, int slot, LAS unsigned char* lds) const { fill_rs(RS_TAB(lds, slot), ssq1 + (size_t)u.pm * BM, 1, 1.f / 2048.f); }
;     __device__ __forceinline__ void prep(const Unit& u, int slot, LAS unsigned char* lds) const { fill_rs(RS_TAB(lds, slot), ssqa + (size_t)u.pm * BM * 8, 8, 1.f / 1024.f); }
;     __device__ __forceinline__ void prep(const Unit& u, int slot, LAS unsigned char* lds) const { fill_rs(RS_TAB(lds, slot), ssq2 + (size_t)u.pm * BM * 32, 32, 1.f / 2048.f); }
;     __device__ bool next(int i, Unit& u) const {
;     ...
;             const int k = c - 64, cnt = (k < 64) ? 5 : 4, start = (k < 64) ? 64 + 5 * k : 384 + 4 * (k - 64);
;             if (i >= cnt) return false; small(start + i, u); return true;
; template <class Prob, class Epi, class Sched>
; __device__ __forceinline__ void gemm_phase(LAS unsigned char* lds, const Prob& P, const Sched& S, const Epi& E) {
;     ...
;     Unit cur, nxt; int ui = 0;
;     if (!S.next(0, cur)) return;
;     Acc acc;
;     bf16x8 At[4][2], B0[2][2], B1[2][2];
;     const char* cA; const char* cB; int nt;
;     P.ptrs(cur, cA, cB, nt);
;     int slot = 0;
;     E.prep(cur, 0, lds); E.prefetch(cur, 0, lds, wid, lane);
;     if (Epi::HAS_INIT) { PG8_BAR; asm volatile("" ::: "memory"); E.init(acc, cur, 0, wr, wc, fr, fq, lds); }
;     else {
; #pragma unroll
;         for (int a = 0; a < 2; ++a)
; #pragma unroll
;             for (int b = 0; b < 2; ++b)
; #pragma unroll
;                 for (int m = 0; m < 4; ++m)
; #pragma unroll
;                     for (int n = 0; n < 2; ++n) acc[a][b][m][n] = (f32x4){0.f, 0.f, 0.f, 0.f};
;     }
;     PG8_STAGE(PG8_SB(0, 0), cB, voffB); PG8_STAGE(PG8_SB(0, 1), cB + hstepB, voffB); PG8_STAGE(PG8_SA(0, 0), cA, voffA); PG8_STAGE(PG8_SA(0, 1), cA + hstepA, voffA);
;     if (wr == 1) PG8_BAR;
;     PG8_WAIT_V(2); PG8_BAR;
;     PG8_STAGE(PG8_SB(1, 0), cB + kstep, voffB); PG8_STAGE(PG8_SA(1, 0), cA + kstep, voffA); PG8_STAGE(PG8_SB(1, 1), cB + hstepB + kstep, voffB);
;     PG8_WAIT_V(6); PG8_BAR;
.LBB0_412:
	s_and_b64 s[4:5], s[4:5], exec
	s_cselect_b32 s4, 4, 4
	v_writelane_b32 v247, s4, 36
	s_mul_hi_i32 s4, s96, 0x2aaaaaab
	s_lshr_b32 s5, s4, 31
	s_add_i32 s4, s4, s5
	v_writelane_b32 v247, s4, 37
	s_mul_i32 s4, s4, 6
	v_and_b32_e32 v2, 48, v0
	v_lshlrev_b32_e32 v3, 6, v0
	s_movk_i32 s8, 0x3c0
	s_sub_i32 s4, s96, s4
	v_and_or_b32 v2, v3, s8, v2
	v_and_b32_e32 v3, 32, v224
	v_writelane_b32 v247, s4, 38
	s_and_b32 s8, s6, 3
	s_lshl_b32 s4, s7, 13
	s_lshl_b32 s56, s7, 6
	v_bitop3_b32 v4, v2, s4, v3 bitop3:0xde
	s_lshl_b32 s57, s8, 5
	s_lshl_b32 s4, s8, 12
	s_add_i32 s62, s41, 0x18000
	v_bitop3_b32 v2, s4, v2, v3 bitop3:0xf6
	s_add_u32 s4, s80, 0x80
	s_waitcnt vmcnt(2)
	s_barrier
	s_addc_u32 s5, s81, 0
	s_mov_b32 m0, s62
	s_nop 0
	global_load_lds_dwordx4 v216, s[4:5]
	s_nop 1
	s_add_i32 s63, s41, 0x1a000
	s_add_i32 s70, s41, 0x8000
	s_mov_b32 m0, s63
	s_nop 0
	global_load_lds_dwordx4 v218, s[4:5]
	s_nop 1
	s_add_u32 s4, s78, 0x80
	s_addc_u32 s5, s79, 0
	s_mov_b32 m0, s70
	s_nop 0
	global_load_lds_dwordx4 v1, s[4:5]
	s_nop 1
	s_add_i32 s71, s41, 0xa000
	s_add_i32 s44, s41, 0x1c000
	s_mov_b32 m0, s71
	s_nop 0
	global_load_lds_dwordx4 v217, s[4:5]
	s_nop 1
	s_add_u32 s4, s80, 0x80080
	s_addc_u32 s5, s81, 0
	s_add_i32 s45, s41, 0x1e000
	s_add_i32 s46, s41, 0xc000
	s_mov_b32 m0, s44
	s_nop 0
	global_load_lds_dwordx4 v216, s[4:5]
	s_nop 1
	s_cmpk_lt_u32 s34, 0x100
	s_mov_b32 m0, s45
	s_nop 0
	global_load_lds_dwordx4 v218, s[4:5]
	s_nop 1
	s_cselect_b64 s[4:5], -1, 0
	v_writelane_b32 v247, s4, 39
	s_cmp_lt_u32 s8, 2
	s_waitcnt vmcnt(6)
	s_cselect_b64 s[58:59], -1, 0
	v_writelane_b32 v247, s5, 40
	s_bfe_u32 s4, s6, 0x10001
	v_writelane_b32 v247, s4, 41
	s_lshl_b32 s4, s6, 4
	s_waitcnt vmcnt(5)
	v_mov_b32_e32 v131, 0
	s_and_b32 s4, s4, 16
	s_add_i32 s47, s41, 0xe000
	v_add_u32_e32 v219, 0, v2
	v_add_u32_e32 v220, 0, v4
	s_mov_b64 s[76:77], 0x100
	s_movk_i32 s60, 0xc00
	v_mov_b32_e32 v221, 0x358637bd
	s_mov_b32 s61, 0
	s_mov_b32 s43, 0
	v_mov_b32_e32 v66, v131
	v_mov_b32_e32 v67, v131
	v_mov_b32_e32 v68, v131
	v_mov_b32_e32 v69, v131
	v_mov_b32_e32 v70, v131
	v_mov_b32_e32 v71, v131
	v_mov_b32_e32 v72, v131
	v_mov_b32_e32 v73, v131
	v_mov_b32_e32 v74, v131
	v_mov_b32_e32 v75, v131
	v_mov_b32_e32 v76, v131
	v_mov_b32_e32 v77, v131
	v_mov_b32_e32 v78, v131
	v_mov_b32_e32 v79, v131
	v_mov_b32_e32 v80, v131
	v_mov_b32_e32 v81, v131
	v_mov_b32_e32 v82, v131
	v_mov_b32_e32 v83, v131
	v_mov_b32_e32 v84, v131
	v_mov_b32_e32 v85, v131
	v_mov_b32_e32 v86, v131
	v_mov_b32_e32 v87, v131
	v_mov_b32_e32 v88, v131
	v_mov_b32_e32 v89, v131
	v_mov_b32_e32 v90, v131
	v_mov_b32_e32 v91, v131
	v_mov_b32_e32 v92, v131
	v_mov_b32_e32 v93, v131
	v_mov_b32_e32 v94, v131
	v_mov_b32_e32 v95, v131
	v_mov_b32_e32 v96, v131
	v_mov_b32_e32 v97, v131
	v_mov_b32_e32 v98, v131
	v_mov_b32_e32 v99, v131
	v_mov_b32_e32 v100, v131
	v_mov_b32_e32 v101, v131
	v_mov_b32_e32 v102, v131
	v_mov_b32_e32 v103, v131
	v_mov_b32_e32 v104, v131
	v_mov_b32_e32 v105, v131
	v_mov_b32_e32 v106, v131
	v_mov_b32_e32 v107, v131
	v_mov_b32_e32 v108, v131
	v_mov_b32_e32 v109, v131
	v_mov_b32_e32 v110, v131
	v_mov_b32_e32 v111, v131
	v_mov_b32_e32 v112, v131
	v_mov_b32_e32 v113, v131
	v_mov_b32_e32 v114, v131
	v_mov_b32_e32 v115, v131
	v_mov_b32_e32 v116, v131
	v_mov_b32_e32 v117, v131
	v_mov_b32_e32 v118, v131
	v_mov_b32_e32 v119, v131
	v_mov_b32_e32 v120, v131
	v_mov_b32_e32 v121, v131
	v_mov_b32_e32 v122, v131
	v_mov_b32_e32 v123, v131
	v_mov_b32_e32 v124, v131
	v_mov_b32_e32 v125, v131
	v_mov_b32_e32 v126, v131
	v_mov_b32_e32 v127, v131
	v_mov_b32_e32 v128, v131
	v_mov_b32_e32 v129, v131
	v_mov_b32_e32 v6, v131
	v_mov_b32_e32 v7, v131
	v_mov_b32_e32 v8, v131
	v_mov_b32_e32 v9, v131
	v_mov_b32_e32 v10, v131
	v_mov_b32_e32 v11, v131
	v_mov_b32_e32 v12, v131
	v_mov_b32_e32 v13, v131
	v_mov_b32_e32 v14, v131
	v_mov_b32_e32 v15, v131
	v_mov_b32_e32 v16, v131
	v_mov_b32_e32 v17, v131
	v_mov_b32_e32 v18, v131
	v_mov_b32_e32 v19, v131
	v_mov_b32_e32 v20, v131
	v_mov_b32_e32 v21, v131
	v_mov_b32_e32 v22, v131
	v_mov_b32_e32 v23, v131
	v_mov_b32_e32 v24, v131
	v_mov_b32_e32 v25, v131
	v_mov_b32_e32 v26, v131
	v_mov_b32_e32 v27, v131
	v_mov_b32_e32 v28, v131
	v_mov_b32_e32 v29, v131
	v_mov_b32_e32 v30, v131
	v_mov_b32_e32 v31, v131
	v_mov_b32_e32 v32, v131
	v_mov_b32_e32 v33, v131
	v_mov_b32_e32 v34, v131
	v_mov_b32_e32 v35, v131
	v_mov_b32_e32 v36, v131
	v_mov_b32_e32 v37, v131
	v_mov_b32_e32 v38, v131
	s_waitcnt lgkmcnt(0)
	v_mov_b32_e32 v39, v131
	v_mov_b32_e32 v40, v131
	v_mov_b32_e32 v41, v131
	v_mov_b32_e32 v42, v131
	v_mov_b32_e32 v43, v131
	v_mov_b32_e32 v44, v131
	v_mov_b32_e32 v45, v131
	v_mov_b32_e32 v46, v131
	v_mov_b32_e32 v47, v131
	v_mov_b32_e32 v48, v131
	v_mov_b32_e32 v49, v131
	v_mov_b32_e32 v50, v131
	v_mov_b32_e32 v51, v131
	v_mov_b32_e32 v52, v131
	v_mov_b32_e32 v53, v131
	v_mov_b32_e32 v54, v131
	v_mov_b32_e32 v55, v131
	v_mov_b32_e32 v56, v131
	v_mov_b32_e32 v57, v131
	v_mov_b32_e32 v58, v131
	v_mov_b32_e32 v59, v131
	v_mov_b32_e32 v60, v131
	v_mov_b32_e32 v61, v131
	v_mov_b32_e32 v62, v131
	v_mov_b32_e32 v63, v131
	v_mov_b32_e32 v64, v131
	v_mov_b32_e32 v65, v131
	v_mov_b32_e32 v2, v131
	v_mov_b32_e32 v3, v131
	v_mov_b32_e32 v4, v131
	v_mov_b32_e32 v5, v131
	s_barrier
	v_writelane_b32 v247, s4, 42
	s_branch .LBB0_415

;     __device__ bool next(int i, Unit& u) const { if (i >= 2) return false; const int j = c >> 3; u.pm = i * 32 + (c & 7) * 4 + (j >> 3); u.pn = j & 7; u.ty = 0; return true; }
;     __device__ static void small(int s, Unit& u) { if (s < 384) { u.ty = 0; u.pm = s / 6; u.pn = s % 6; } else { s -= 384; u.ty = 1; u.pm = s >> 3; u.pn = s & 7; } }
;     __device__ bool next(int i, Unit& u) const {
;         if (G == 256) {
;             if (c < 64) { if (i == 0) { u.ty = 2; u.pm = c; u.pn = 0; return true; } if (i == 1) { small(c, u); return true; } return false; }
;             const int k = c - 64, cnt = (k < 64) ? 5 : 4, start = (k < 64) ? 64 + 5 * k : 384 + 4 * (k - 64);
;             if (i >= cnt) return false; small(start + i, u); return true;
;         }
;         const int L = i * G + c; if (L >= 960) return false;
;         if (L < 64) { u.ty = 2; u.pm = L; u.pn = 0; } else small(L - 64, u);
;         return true;
.LBB0_432:
	s_andn2_b64 vcc, exec, s[4:5]
	s_cbranch_vccnz .LBB0_439
	s_cmp_lt_i32 s43, 0
	s_mov_b64 s[4:5], -1
	s_cbranch_scc1 .LBB0_435
	s_mov_b64 s[4:5], 0
	s_cmp_eq_u32 s43, 0
	s_mov_b64 s[92:93], 0
	s_mov_b32 s84, s10
	s_mov_b32 s82, s9
	s_mov_b32 s40, s8
	s_cbranch_scc1 .LBB0_685
	s_cmp_eq_u32 s43, 1
	s_cbranch_scc1 .Lp2_i2

;     __device__ bool next(int i, Unit& u) const { if (i >= 2) return false; const int j = c >> 3; u.pm = i * 32 + (c & 7) * 4 + (j >> 3); u.pn = j & 7; u.ty = 0; return true; }
; template <class Prob, class Epi, class Sched>
; __device__ __forceinline__ void gemm_phase(LAS unsigned char* lds, const Prob& P, const Sched& S, const Epi& E) {
;     ...
;         const bool has_next = S.next(ui + 1, nxt);
;         const char* nA = cA; const char* nB = cB; int nnt = nt;
;         if (has_next) P.ptrs(nxt, nA, nB, nnt);
;         for (int t = 0; t < nt; t += 2) {
;             const bool last = (t == nt - 2);
;             if (Epi::MID_T >= 0) { if (t == Epi::MID_T) E.mid(acc, cur, slot, wr, wc, fr, fq, lds); }
;             const char* a1 = cA + (size_t)(t + 1) * kstep;
;             const char* a2 = last ? nA : cA + (size_t)(t + 2) * kstep; const char* b2 = last ? nB : cB + (size_t)(t + 2) * kstep;
.LBB0_450:
	s_add_u32 s49, s78, 0x80000
	s_addc_u32 s54, s79, 0
	s_add_i32 s55, s53, -2
	s_mov_b32 s6, 0
	s_mov_b64 s[4:5], 0x100
	s_cmp_eq_u32 s42, 2
	s_cbranch_scc1 .Lkr451

; #define PG8_BAR __builtin_amdgcn_s_barrier()
; template <class Prob, class Epi, class Sched>
; __device__ __forceinline__ void gemm_phase(LAS unsigned char* lds, const Prob& P, const Sched& S, const Epi& E) {
;     ...
;         if (wr == 0) PG8_BAR;
;         E(acc, cur, slot, ui & 1, wr, wc, fr, fq, lds);
;         if (!has_next) break;
.Lkr_after:
	v_readlane_b32 s4, v247, 39
	v_readlane_b32 s5, v247, 40
	s_and_b64 vcc, exec, s[4:5]
	s_cbranch_vccz .LBB0_454
	s_barrier

;     __device__ bool next(int i, Unit& u) const { if (i >= 2) return false; const int j = c >> 3; u.pm = i * 32 + (c & 7) * 4 + (j >> 3); u.pn = j & 7; u.ty = 0; return true; }
;     __device__ static void small(int s, Unit& u) { if (s < 384) { u.ty = 0; u.pm = s / 6; u.pn = s % 6; } else { s -= 384; u.ty = 1; u.pm = s >> 3; u.pn = s & 7; } }
; #define PG8_STAGE(bufoff, gbase, voff) do { _Pragma("unroll") for (int _i = 0; _i < 2; ++_i) { \
;         const unsigned m0v_ = (unsigned)(uintptr_t)(lds + (bufoff) + ldsw + _i * 8192); \
;         asm volatile("s_mov_b32 m0, %0\n\ts_nop 0\n\tglobal_load_lds_dwordx4 %1, %2\n\ts_nop 1" :: "s"(m0v_), "v"((voff)[_i]), "s"((const char*)(gbase)) : "m0", "memory"); } } while (0)
; #define PG8_WAIT_V(n) asm volatile("s_waitcnt vmcnt(" #n ")" ::: "memory")
; #define PG8_WAIT_L(n) asm volatile("s_waitcnt lgkmcnt(" #n ")" ::: "memory")
;     __device__ bool next(int i, Unit& u) const {
;         if (G == 256) {
;             if (c < 64) { if (i == 0) { u.ty = 2; u.pm = c; u.pn = 0; return true; } if (i == 1) { small(c, u); return true; } return false; }
; template <class Prob, class Epi, class Sched>
; __device__ __forceinline__ void gemm_phase(LAS unsigned char* lds, const Prob& P, const Sched& S, const Epi& E) {
;     ...
;         for (int t = 0; t < nt; t += 2) {
;             const bool last = (t == nt - 2);
;             if (Epi::MID_T >= 0) { if (t == Epi::MID_T) E.mid(acc, cur, slot, wr, wc, fr, fq, lds); }
;             const char* a1 = cA + (size_t)(t + 1) * kstep;
;             const char* a2 = last ? nA : cA + (size_t)(t + 2) * kstep; const char* b2 = last ? nB : cB + (size_t)(t + 2) * kstep;
;             const char* a3 = a2 + kstep; const char* b3 = b2 + kstep;
;             PG8_LDB(B0, 0, 0); PG8_LDB(B1, 0, 1); PG8_SCHED; PG8_LDA(At, 0, 0); PG8_STAGE(PG8_SA(1, 1), a1 + hstepA, voffA);
;             PG8_WAIT_V(8); PG8_WAIT_L(0); PG8_BAR; __builtin_amdgcn_s_setprio(1); PG8_MMA(0, 0, At, B0); PG8_MMA(0, 1, At, B1); __builtin_amdgcn_s_setprio(0); PG8_BAR; PG8_SCHED;
;             PG8_LDA(At, 0, 1); PG8_STAGE(PG8_SB(0, 0), b2, voffB); PG8_STAGE(PG8_SB(0, 1), b2 + hstepB, voffB); PG8_STAGE(PG8_SA(0, 0), a2, voffA);
;             PG8_WAIT_V(8); PG8_WAIT_L(0); PG8_BAR; __builtin_amdgcn_s_setprio(1); PG8_MMA(1, 0, At, B0); PG8_MMA(1, 1, At, B1); __builtin_amdgcn_s_setprio(0); PG8_BAR; PG8_SCHED;
.Lp2_i2:
	s_add_i32 s6, s96, 64
	s_mul_i32 s7, s6, 0xaaab
	s_lshr_b32 s84, s7, 18
	s_mul_i32 s7, s84, 6
	s_sub_i32 s82, s6, s7
	s_mov_b32 s40, 0
	s_mov_b64 s[92:93], -1
	s_branch .LBB0_439
.Lkr451:
	v_add_u32_e32 v130, 0x10000, v219
	s_add_i32 s68, s6, 2
	ds_read_b128 v[132:135], v130
	s_waitcnt vmcnt(4)
	ds_read_b128 v[136:139], v130 offset:1024
	ds_read_b128 v[140:143], v130 offset:2048
	s_waitcnt vmcnt(3)
	ds_read_b128 v[144:147], v130 offset:3072
	v_add_u32_e32 v130, 0x14000, v219
	s_add_u32 s7, s78, s4
	s_waitcnt vmcnt(2)
	ds_read_b128 v[148:151], v130
	s_waitcnt vmcnt(0)
	ds_read_b128 v[152:155], v130 offset:1024
	ds_read_b128 v[156:159], v130 offset:2048
	ds_read_b128 v[160:163], v130 offset:3072
	s_addc_u32 s8, s79, s5
	s_add_u32 s9, s80, s4
	s_addc_u32 s74, s81, s5
	s_cmp_eq_u32 s55, s6
	s_cselect_b32 s10, s88, s7
	s_cselect_b32 s11, s89, s8
	s_cselect_b32 s8, s90, s9
	s_cselect_b32 s9, s91, s74
	s_add_u32 s6, s10, 0x80
	s_addc_u32 s7, s11, 0
	ds_read_b128 v[164:167], v220
	ds_read_b128 v[168:171], v220 offset:1024
	ds_read_b128 v[172:175], v220 offset:2048
	ds_read_b128 v[176:179], v220 offset:3072
	ds_read_b128 v[180:183], v220 offset:4096
	ds_read_b128 v[184:187], v220 offset:5120
	ds_read_b128 v[188:191], v220 offset:6144
	ds_read_b128 v[192:195], v220 offset:7168
	s_add_u32 s74, s49, s4
	s_addc_u32 s75, s54, s5
	s_add_u32 s74, s74, 0xffffff80
	s_addc_u32 s75, s75, -1
	s_sub_u32 s98, s74, 0x80000
	s_subb_u32 s99, s75, 0
	s_mov_b32 m0, s70
	s_nop 0
	global_load_lds_dwordx4 v1, s[98:99]
	s_nop 1
	s_nop 0
	s_mov_b32 m0, s71
	s_nop 0
	global_load_lds_dwordx4 v217, s[98:99]
	s_nop 1
	s_mov_b32 m0, s46
	s_nop 0
	global_load_lds_dwordx4 v1, s[74:75]
	s_nop 1
	s_nop 0
	s_mov_b32 m0, s47
	s_nop 0
	global_load_lds_dwordx4 v217, s[74:75]
	s_nop 1
	s_waitcnt vmcnt(8)
	s_waitcnt lgkmcnt(0)
	s_barrier
	s_setprio 1
	s_waitcnt lgkmcnt(7)
	v_mfma_f32_16x16x32_bf16 v[2:5], v[132:135], v[164:167], v[2:5]
	v_mfma_f32_16x16x32_bf16 v[62:65], v[140:143], v[164:167], v[62:65]
	s_waitcnt lgkmcnt(5)
	v_mfma_f32_16x16x32_bf16 v[58:61], v[132:135], v[172:175], v[58:61]
	v_mfma_f32_16x16x32_bf16 v[54:57], v[140:143], v[172:175], v[54:57]
	s_waitcnt lgkmcnt(3)
	v_mfma_f32_16x16x32_bf16 v[50:53], v[132:135], v[180:183], v[50:53]
	v_mfma_f32_16x16x32_bf16 v[46:49], v[140:143], v[180:183], v[46:49]
	s_waitcnt lgkmcnt(1)
	v_mfma_f32_16x16x32_bf16 v[42:45], v[132:135], v[188:191], v[42:45]
	v_mfma_f32_16x16x32_bf16 v[38:41], v[140:143], v[188:191], v[38:41]
	v_mfma_f32_16x16x32_bf16 v[2:5], v[136:139], v[168:171], v[2:5]
	v_mfma_f32_16x16x32_bf16 v[62:65], v[144:147], v[168:171], v[62:65]
	v_mfma_f32_16x16x32_bf16 v[58:61], v[136:139], v[176:179], v[58:61]
	v_mfma_f32_16x16x32_bf16 v[54:57], v[144:147], v[176:179], v[54:57]
	v_mfma_f32_16x16x32_bf16 v[50:53], v[136:139], v[184:187], v[50:53]
	v_mfma_f32_16x16x32_bf16 v[46:49], v[144:147], v[184:187], v[46:49]
	s_waitcnt lgkmcnt(0)
	v_mfma_f32_16x16x32_bf16 v[42:45], v[136:139], v[192:195], v[42:45]
	v_mfma_f32_16x16x32_bf16 v[38:41], v[144:147], v[192:195], v[38:41]
	s_setprio 0
	s_barrier
	ds_read_b128 v[164:167], v220 offset:16384
	ds_read_b128 v[168:171], v220 offset:17408
	ds_read_b128 v[172:175], v220 offset:18432
	ds_read_b128 v[176:179], v220 offset:19456
	ds_read_b128 v[180:183], v220 offset:20480
	ds_read_b128 v[184:187], v220 offset:21504
	ds_read_b128 v[188:191], v220 offset:22528
	ds_read_b128 v[192:195], v220 offset:23552
	s_mov_b32 m0, s67
	s_nop 0
	global_load_lds_dwordx4 v216, s[8:9]
	s_nop 1
	s_add_u32 s74, s8, 0x80000
	s_mov_b32 m0, s0
	s_nop 0
	global_load_lds_dwordx4 v218, s[8:9]
	s_nop 1
	s_addc_u32 s75, s9, 0
	s_mov_b32 m0, s1
	s_nop 0
	global_load_lds_dwordx4 v216, s[74:75]
	s_nop 1
	s_nop 0
	s_mov_b32 m0, s35
	s_nop 0
	global_load_lds_dwordx4 v218, s[74:75]
	s_nop 1
	s_nop 0
	s_waitcnt vmcnt(6)
	s_waitcnt lgkmcnt(0)
	s_barrier
	s_setprio 1
	s_waitcnt lgkmcnt(7)
	v_mfma_f32_16x16x32_bf16 v[126:129], v[132:135], v[164:167], v[126:129]
	v_mfma_f32_16x16x32_bf16 v[122:125], v[140:143], v[164:167], v[122:125]
	s_waitcnt lgkmcnt(5)
	v_mfma_f32_16x16x32_bf16 v[118:121], v[132:135], v[172:175], v[118:121]
	v_mfma_f32_16x16x32_bf16 v[114:117], v[140:143], v[172:175], v[114:117]
	s_waitcnt lgkmcnt(3)
	v_mfma_f32_16x16x32_bf16 v[110:113], v[132:135], v[180:183], v[110:113]
	v_mfma_f32_16x16x32_bf16 v[106:109], v[140:143], v[180:183], v[106:109]
	s_waitcnt lgkmcnt(1)
	v_mfma_f32_16x16x32_bf16 v[102:105], v[132:135], v[188:191], v[102:105]
	v_mfma_f32_16x16x32_bf16 v[98:101], v[140:143], v[188:191], v[98:101]
	v_mfma_f32_16x16x32_bf16 v[126:129], v[136:139], v[168:171], v[126:129]
	v_mfma_f32_16x16x32_bf16 v[122:125], v[144:147], v[168:171], v[122:125]
	v_mfma_f32_16x16x32_bf16 v[118:121], v[136:139], v[176:179], v[118:121]
	v_mfma_f32_16x16x32_bf16 v[114:117], v[144:147], v[176:179], v[114:117]
	v_mfma_f32_16x16x32_bf16 v[110:113], v[136:139], v[184:187], v[110:113]
	v_mfma_f32_16x16x32_bf16 v[106:109], v[144:147], v[184:187], v[106:109]
	s_waitcnt lgkmcnt(0)
	v_mfma_f32_16x16x32_bf16 v[102:105], v[136:139], v[192:195], v[102:105]
	v_mfma_f32_16x16x32_bf16 v[98:101], v[144:147], v[192:195], v[98:101]
	s_setprio 0
	s_barrier
; #define PG8_STAGE(bufoff, gbase, voff) do { _Pragma("unroll") for (int _i = 0; _i < 2; ++_i) { \
;         const unsigned m0v_ = (unsigned)(uintptr_t)(lds + (bufoff) + ldsw + _i * 8192); \
;         asm volatile("s_mov_b32 m0, %0\n\ts_nop 0\n\tglobal_load_lds_dwordx4 %1, %2\n\ts_nop 1" :: "s"(m0v_), "v"((voff)[_i]), "s"((const char*)(gbase)) : "m0", "memory"); } } while (0)
; #define PG8_LDA(dst, b, h) do { _Pragma("unroll") for (int m = 0; m < 4; ++m) _Pragma("unroll") for (int k = 0; k < 2; ++k) dst[m][k] = *(const LAS bf16x8*)(lds + PG8_SA(b, h) + aoff + m * 2048 + k * 1024); } while (0)
; #define PG8_LDB(dst, b, h) do { _Pragma("unroll") for (int n = 0; n < 2; ++n) _Pragma("unroll") for (int k = 0; k < 2; ++k) dst[n][k] = *(const LAS bf16x8*)(lds + PG8_SB(b, h) + boff + n * 2048 + k * 1024); } while (0)
; #define PG8_MMA(ai, bj, At, Bt) do { _Pragma("unroll") for (int m = 0; m < 4; ++m) _Pragma("unroll") for (int n = 0; n < 2; ++n) _Pragma("unroll") for (int k = 0; k < 2; ++k) \
;         acc[ai][bj][m][n] = __builtin_amdgcn_mfma_f32_16x16x32_bf16(Bt[n][k], At[m][k], acc[ai][bj][m][n], 0, 0, 0); } while (0)
; #define PG8_WAIT_V(n) asm volatile("s_waitcnt vmcnt(" #n ")" ::: "memory")
; #define PG8_WAIT_L(n) asm volatile("s_waitcnt lgkmcnt(" #n ")" ::: "memory")
; #define PG8_BAR __builtin_amdgcn_s_barrier()
; #define PG8_SCHED __builtin_amdgcn_sched_barrier(0)
; template <class Prob, class Epi, class Sched>
; __device__ __forceinline__ void gemm_phase(LAS unsigned char* lds, const Prob& P, const Sched& S, const Epi& E) {
;     ...
;             PG8_LDB(B0, 1, 0); PG8_LDB(B1, 1, 1); PG8_SCHED; PG8_LDA(At, 1, 0); PG8_STAGE(PG8_SA(0, 1), a2 + hstepA, voffA);
;             PG8_WAIT_V(8); PG8_WAIT_L(0); PG8_BAR; __builtin_amdgcn_s_setprio(1); PG8_MMA(0, 0, At, B0); PG8_MMA(0, 1, At, B1); __builtin_amdgcn_s_setprio(0); PG8_BAR; PG8_SCHED;
;             PG8_LDA(At, 1, 1); PG8_STAGE(PG8_SB(1, 0), b3, voffB); PG8_STAGE(PG8_SB(1, 1), b3 + hstepB, voffB); PG8_STAGE(PG8_SA(1, 0), a3, voffA);
;             PG8_WAIT_V(8); PG8_WAIT_L(0); PG8_BAR; __builtin_amdgcn_s_setprio(1); PG8_MMA(1, 0, At, B0); PG8_MMA(1, 1, At, B1); __builtin_amdgcn_s_setprio(0); PG8_BAR; PG8_SCHED;
;         }
	v_add_u32_e32 v130, 0x18000, v219
	ds_read_b128 v[132:135], v130
	ds_read_b128 v[136:139], v130 offset:1024
	ds_read_b128 v[140:143], v130 offset:2048
	ds_read_b128 v[144:147], v130 offset:3072
	v_add_u32_e32 v130, 0x1c000, v219
	ds_read_b128 v[148:151], v130
	ds_read_b128 v[152:155], v130 offset:1024
	ds_read_b128 v[156:159], v130 offset:2048
	ds_read_b128 v[160:163], v130 offset:3072
	ds_read_b128 v[164:167], v220 offset:32768
	ds_read_b128 v[168:171], v220 offset:33792
	ds_read_b128 v[172:175], v220 offset:34816
	ds_read_b128 v[176:179], v220 offset:35840
	ds_read_b128 v[180:183], v220 offset:36864
	ds_read_b128 v[184:187], v220 offset:37888
	ds_read_b128 v[188:191], v220 offset:38912
	ds_read_b128 v[192:195], v220 offset:39936
	s_mov_b32 m0, s41
	s_nop 0
	global_load_lds_dwordx4 v1, s[10:11]
	s_nop 1
	s_nop 0
	s_mov_b32 m0, s3
	s_nop 0
	global_load_lds_dwordx4 v217, s[10:11]
	s_nop 1
	s_add_u32 s10, s10, 0x80000
	s_addc_u32 s11, s11, 0
	s_mov_b32 m0, s64
	s_nop 0
	global_load_lds_dwordx4 v1, s[10:11]
	s_nop 1
	s_nop 0
	s_mov_b32 m0, s65
	s_nop 0
	global_load_lds_dwordx4 v217, s[10:11]
	s_nop 1
	s_waitcnt vmcnt(8)
	s_waitcnt lgkmcnt(0)
	s_barrier
	s_setprio 1
	s_waitcnt lgkmcnt(7)
	v_mfma_f32_16x16x32_bf16 v[2:5], v[132:135], v[164:167], v[2:5]
	v_mfma_f32_16x16x32_bf16 v[62:65], v[140:143], v[164:167], v[62:65]
	s_waitcnt lgkmcnt(5)
	v_mfma_f32_16x16x32_bf16 v[58:61], v[132:135], v[172:175], v[58:61]
	v_mfma_f32_16x16x32_bf16 v[54:57], v[140:143], v[172:175], v[54:57]
	s_waitcnt lgkmcnt(3)
	v_mfma_f32_16x16x32_bf16 v[50:53], v[132:135], v[180:183], v[50:53]
	v_mfma_f32_16x16x32_bf16 v[46:49], v[140:143], v[180:183], v[46:49]
	s_waitcnt lgkmcnt(1)
	v_mfma_f32_16x16x32_bf16 v[42:45], v[132:135], v[188:191], v[42:45]
	v_mfma_f32_16x16x32_bf16 v[38:41], v[140:143], v[188:191], v[38:41]
	v_mfma_f32_16x16x32_bf16 v[2:5], v[136:139], v[168:171], v[2:5]
	v_mfma_f32_16x16x32_bf16 v[62:65], v[144:147], v[168:171], v[62:65]
	v_mfma_f32_16x16x32_bf16 v[58:61], v[136:139], v[176:179], v[58:61]
	v_mfma_f32_16x16x32_bf16 v[54:57], v[144:147], v[176:179], v[54:57]
	v_mfma_f32_16x16x32_bf16 v[50:53], v[136:139], v[184:187], v[50:53]
	v_mfma_f32_16x16x32_bf16 v[46:49], v[144:147], v[184:187], v[46:49]
	s_waitcnt lgkmcnt(0)
	v_mfma_f32_16x16x32_bf16 v[42:45], v[136:139], v[192:195], v[42:45]
	v_mfma_f32_16x16x32_bf16 v[38:41], v[144:147], v[192:195], v[38:41]
	s_setprio 0
	s_barrier
	ds_read_b128 v[164:167], v220 offset:49152
	ds_read_b128 v[168:171], v220 offset:50176
	ds_read_b128 v[172:175], v220 offset:51200
	ds_read_b128 v[176:179], v220 offset:52224
	ds_read_b128 v[180:183], v220 offset:53248
	ds_read_b128 v[184:187], v220 offset:54272
	ds_read_b128 v[188:191], v220 offset:55296
	ds_read_b128 v[192:195], v220 offset:56320
	s_add_u32 s10, s8, 0x80
	s_addc_u32 s11, s9, 0
	s_mov_b32 m0, s62
	s_nop 0
	global_load_lds_dwordx4 v216, s[10:11]
	s_nop 1
	s_add_u32 s8, s8, 0x80080
	s_mov_b32 m0, s63
	s_nop 0
	global_load_lds_dwordx4 v218, s[10:11]
	s_nop 1
	s_addc_u32 s9, s9, 0
	s_mov_b32 m0, s44
	s_nop 0
	global_load_lds_dwordx4 v216, s[8:9]
	s_nop 1
	s_nop 0
	s_mov_b32 m0, s45
	s_nop 0
	global_load_lds_dwordx4 v218, s[8:9]
	s_nop 1
	s_nop 0
	s_waitcnt vmcnt(6)
	s_waitcnt lgkmcnt(0)
	s_barrier
	s_setprio 1
	s_waitcnt lgkmcnt(7)
	v_mfma_f32_16x16x32_bf16 v[126:129], v[132:135], v[164:167], v[126:129]
	v_mfma_f32_16x16x32_bf16 v[122:125], v[140:143], v[164:167], v[122:125]
	s_waitcnt lgkmcnt(5)
	v_mfma_f32_16x16x32_bf16 v[118:121], v[132:135], v[172:175], v[118:121]
	v_mfma_f32_16x16x32_bf16 v[114:117], v[140:143], v[172:175], v[114:117]
	s_waitcnt lgkmcnt(3)
	v_mfma_f32_16x16x32_bf16 v[110:113], v[132:135], v[180:183], v[110:113]
	v_mfma_f32_16x16x32_bf16 v[106:109], v[140:143], v[180:183], v[106:109]
	s_waitcnt lgkmcnt(1)
	v_mfma_f32_16x16x32_bf16 v[102:105], v[132:135], v[188:191], v[102:105]
	v_mfma_f32_16x16x32_bf16 v[98:101], v[140:143], v[188:191], v[98:101]
	v_mfma_f32_16x16x32_bf16 v[126:129], v[136:139], v[168:171], v[126:129]
	v_mfma_f32_16x16x32_bf16 v[122:125], v[144:147], v[168:171], v[122:125]
	v_mfma_f32_16x16x32_bf16 v[118:121], v[136:139], v[176:179], v[118:121]
	v_mfma_f32_16x16x32_bf16 v[114:117], v[144:147], v[176:179], v[114:117]
	v_mfma_f32_16x16x32_bf16 v[110:113], v[136:139], v[184:187], v[110:113]
	v_mfma_f32_16x16x32_bf16 v[106:109], v[144:147], v[184:187], v[106:109]
	s_waitcnt lgkmcnt(0)
	v_mfma_f32_16x16x32_bf16 v[102:105], v[136:139], v[192:195], v[102:105]
	v_mfma_f32_16x16x32_bf16 v[98:101], v[144:147], v[192:195], v[98:101]
	s_setprio 0
	s_barrier
	s_add_u32 s4, s4, 0x100
	s_addc_u32 s5, s5, 0
	s_cmp_ge_i32 s68, s53
	s_mov_b32 s6, s68
	s_cbranch_scc0 .Lkr451
	s_branch .Lkr_after
